# permlane32_swap row-max exchange, v_mov_b64 for score init and accumulator zeroing
# speedup vs baseline: 1.0277x; 1.0045x over previous
; template <class Epi, class Sched, bool ALIGN_EPI = false, bool SP2 = false>
; __device__ __forceinline__ void gemm_phase(LAS unsigned char* lds, const Gemm g, const Sched& S, const Epi& E) {
;     ...
;     f32x4 acc[2][2][4][2];
; #pragma unroll
;     for (int a = 0; a < 2; ++a)
; #pragma unroll
;         for (int b = 0; b < 2; ++b)
; #pragma unroll
;             for (int m = 0; m < 4; ++m)
; #pragma unroll
;                 for (int n = 0; n < 2; ++n) acc[a][b][m][n] = (f32x4){0.f, 0.f, 0.f, 0.f};
.LBB0_40:
	s_add_u32 s69, s44, 0x100
	v_mov_b64_e32 v[0:1], 0
	s_addc_u32 s70, s45, 0
	s_mov_b32 s71, -2
	v_mov_b64_e32 v[2:3], 0
	v_mov_b64_e32 v[4:5], 0
	v_mov_b64_e32 v[6:7], 0
	v_mov_b64_e32 v[8:9], 0
	v_mov_b64_e32 v[10:11], 0
	v_mov_b64_e32 v[12:13], 0
	v_mov_b64_e32 v[14:15], 0
	v_mov_b64_e32 v[24:25], 0
	v_mov_b64_e32 v[26:27], 0
	v_mov_b64_e32 v[28:29], 0
	v_mov_b64_e32 v[30:31], 0
	v_mov_b64_e32 v[40:41], 0
	v_mov_b64_e32 v[42:43], 0
	v_mov_b64_e32 v[44:45], 0
	v_mov_b64_e32 v[46:47], 0
	v_mov_b64_e32 v[16:17], 0
	v_mov_b64_e32 v[18:19], 0
	v_mov_b64_e32 v[20:21], 0
	v_mov_b64_e32 v[22:23], 0
	v_mov_b64_e32 v[32:33], 0
	v_mov_b64_e32 v[34:35], 0
	v_mov_b64_e32 v[36:37], 0
	v_mov_b64_e32 v[38:39], 0
	v_mov_b64_e32 v[48:49], 0
	v_mov_b64_e32 v[50:51], 0
	v_mov_b64_e32 v[52:53], 0
	v_mov_b64_e32 v[54:55], 0
	v_mov_b64_e32 v[56:57], 0
	v_mov_b64_e32 v[58:59], 0
	v_mov_b64_e32 v[60:61], 0
	v_mov_b64_e32 v[62:63], 0
	v_mov_b64_e32 v[64:65], 0
	v_mov_b64_e32 v[66:67], 0
	v_mov_b64_e32 v[68:69], 0
	v_mov_b64_e32 v[70:71], 0
	v_mov_b64_e32 v[72:73], 0
	v_mov_b64_e32 v[74:75], 0
	v_mov_b64_e32 v[76:77], 0
	v_mov_b64_e32 v[78:79], 0
	v_mov_b64_e32 v[88:89], 0
	v_mov_b64_e32 v[90:91], 0
	v_mov_b64_e32 v[92:93], 0
	v_mov_b64_e32 v[94:95], 0
	v_mov_b64_e32 v[104:105], 0
	v_mov_b64_e32 v[106:107], 0
	v_mov_b64_e32 v[108:109], 0
	v_mov_b64_e32 v[110:111], 0
	v_mov_b64_e32 v[80:81], 0
	v_mov_b64_e32 v[82:83], 0
	v_mov_b64_e32 v[84:85], 0
	v_mov_b64_e32 v[86:87], 0
	v_mov_b64_e32 v[96:97], 0
	v_mov_b64_e32 v[98:99], 0
	v_mov_b64_e32 v[100:101], 0
	v_mov_b64_e32 v[102:103], 0
	v_mov_b64_e32 v[112:113], 0
	v_mov_b64_e32 v[114:115], 0
	v_mov_b64_e32 v[116:117], 0
	v_mov_b64_e32 v[118:119], 0
	v_mov_b64_e32 v[120:121], 0
	v_mov_b64_e32 v[122:123], 0
	v_mov_b64_e32 v[124:125], 0
	v_mov_b64_e32 v[126:127], 0

; template <class Epi, class Sched, bool ALIGN_EPI = false, bool SP2 = false>
; __device__ __forceinline__ void gemm_phase(LAS unsigned char* lds, const Gemm g, const Sched& S, const Epi& E) {
;     ...
;         const bool has_next = S.next(ui + 1, nxt);
;         const char* nA = has_next ? (const char*)g.A + (size_t)nxt.pm * g.a_tstep : cA; const char* nB = has_next ? (const char*)g.Bt + (size_t)nxt.pn * tstep : cB;
;     ...
; #pragma unroll
;         for (int a = 0; a < 2; ++a)
; #pragma unroll
;             for (int b = 0; b < 2; ++b)
; #pragma unroll
;                 for (int m = 0; m < 4; ++m)
; #pragma unroll
;                     for (int n = 0; n < 2; ++n) acc[a][b][m][n] = (f32x4){0.f, 0.f, 0.f, 0.f};
;         cur = nxt; cA = nA; cB = nB; ++ui;
.LBB0_68:
	s_ashr_i32 s65, s64, 31
	s_lshl_b64 s[38:39], s[64:65], 19
	v_readlane_b32 s33, v254, 41
	s_add_u32 s68, s33, s38
	v_readlane_b32 s33, v254, 55
	s_addc_u32 s69, s33, s39
	s_and_b64 s[0:1], s[0:1], exec
	s_cselect_b32 s38, s69, s41
	s_cselect_b32 s39, s68, s40
	s_add_u32 s0, s44, 0x40080
	s_addc_u32 s1, s45, 0
	s_add_u32 s43, s40, 0x100
	v_mov_b64_e32 v[0:1], 0
	s_addc_u32 s46, s41, 0
	s_mov_b32 s47, -2
	v_mov_b64_e32 v[2:3], 0
	v_mov_b64_e32 v[32:33], 0
	v_mov_b64_e32 v[34:35], 0
	v_mov_b64_e32 v[12:13], 0
	v_mov_b64_e32 v[14:15], 0
	v_mov_b64_e32 v[44:45], 0
	v_mov_b64_e32 v[46:47], 0
	v_mov_b64_e32 v[64:65], 0
	v_mov_b64_e32 v[66:67], 0
	v_mov_b64_e32 v[96:97], 0
	v_mov_b64_e32 v[98:99], 0
	v_mov_b64_e32 v[72:73], 0
	v_mov_b64_e32 v[74:75], 0
	v_mov_b64_e32 v[104:105], 0
	v_mov_b64_e32 v[106:107], 0
	v_mov_b64_e32 v[88:89], 0
	v_mov_b64_e32 v[90:91], 0
	v_mov_b64_e32 v[80:81], 0
	v_mov_b64_e32 v[82:83], 0
	v_mov_b64_e32 v[28:29], 0
	v_mov_b64_e32 v[30:31], 0
	v_mov_b64_e32 v[16:17], 0
	v_mov_b64_e32 v[18:19], 0
	v_mov_b64_e32 v[4:5], 0
	v_mov_b64_e32 v[6:7], 0
	v_mov_b64_e32 v[36:37], 0
	v_mov_b64_e32 v[38:39], 0
	v_mov_b64_e32 v[8:9], 0
	v_mov_b64_e32 v[10:11], 0
	v_mov_b64_e32 v[40:41], 0
	v_mov_b64_e32 v[42:43], 0
	v_mov_b64_e32 v[48:49], 0
	v_mov_b64_e32 v[50:51], 0
	v_mov_b64_e32 v[20:21], 0
	v_mov_b64_e32 v[22:23], 0
	v_mov_b64_e32 v[52:53], 0
	v_mov_b64_e32 v[54:55], 0
	v_mov_b64_e32 v[24:25], 0
	v_mov_b64_e32 v[26:27], 0
	v_mov_b64_e32 v[56:57], 0
	v_mov_b64_e32 v[58:59], 0
	v_mov_b64_e32 v[60:61], 0
	v_mov_b64_e32 v[62:63], 0
	v_mov_b64_e32 v[68:69], 0
	v_mov_b64_e32 v[70:71], 0
	v_mov_b64_e32 v[100:101], 0
	v_mov_b64_e32 v[102:103], 0
	v_mov_b64_e32 v[76:77], 0
	v_mov_b64_e32 v[78:79], 0
	v_mov_b64_e32 v[108:109], 0
	v_mov_b64_e32 v[110:111], 0
	v_mov_b64_e32 v[112:113], 0
	v_mov_b64_e32 v[114:115], 0
	v_mov_b64_e32 v[84:85], 0
	v_mov_b64_e32 v[86:87], 0
	v_mov_b64_e32 v[116:117], 0
	v_mov_b64_e32 v[118:119], 0
	v_mov_b64_e32 v[92:93], 0
	v_mov_b64_e32 v[94:95], 0
	v_mov_b64_e32 v[120:121], 0
	v_mov_b64_e32 v[122:123], 0
	v_mov_b64_e32 v[124:125], 0
	v_mov_b64_e32 v[126:127], 0

; template <class Epi, class Sched, bool ALIGN_EPI = false, bool SP2 = false>
; __device__ __forceinline__ void gemm_phase(LAS unsigned char* lds, const Gemm g, const Sched& S, const Epi& E) {
;     ...
;         const bool has_next = S.next(ui + 1, nxt);
;         const char* nA = has_next ? (const char*)g.A + (size_t)nxt.pm * g.a_tstep : cA; const char* nB = has_next ? (const char*)g.Bt + (size_t)nxt.pn * tstep : cB;
;     ...
; #pragma unroll
;         for (int a = 0; a < 2; ++a)
; #pragma unroll
;             for (int b = 0; b < 2; ++b)
; #pragma unroll
;                 for (int m = 0; m < 4; ++m)
; #pragma unroll
;                     for (int n = 0; n < 2; ++n) acc[a][b][m][n] = (f32x4){0.f, 0.f, 0.f, 0.f};
;         cur = nxt; cA = nA; cB = nB; ++ui;
.LBB0_152:
	v_readlane_b32 s44, v252, 31
	v_readlane_b32 s45, v252, 32
	s_ashr_i32 s41, s40, 31
	s_mov_b32 s69, -2
	v_mov_b64_e32 v[0:1], s[44:45]
	v_cmp_lt_i64_e32 vcc, s[42:43], v[0:1]
	s_lshl_b64 s[42:43], s[40:41], 19
	v_readlane_b32 s44, v252, 43
	v_readlane_b32 s45, v252, 44
	s_add_u32 s42, s44, s42
	s_addc_u32 s43, s45, s43
	s_and_b64 s[44:45], vcc, exec
	s_cselect_b32 s41, s43, s47
	s_cselect_b32 s65, s42, s46
	s_ashr_i32 s31, s30, 31
	s_lshl_b64 s[44:45], s[30:31], 19
	s_add_u32 s44, s22, s44
	s_addc_u32 s45, s23, s45
	s_and_b64 s[50:51], vcc, exec
	s_cselect_b32 s31, s45, s49
	s_cselect_b32 s66, s44, s48
	s_add_u32 s46, s46, 0x40080
	s_addc_u32 s47, s47, 0
	s_add_u32 s67, s48, 0x100
	v_mov_b64_e32 v[0:1], 0
	s_addc_u32 s68, s49, 0
	v_mov_b64_e32 v[2:3], 0
	v_mov_b64_e32 v[4:5], 0
	v_mov_b64_e32 v[6:7], 0
	v_mov_b64_e32 v[8:9], 0
	v_mov_b64_e32 v[10:11], 0
	v_mov_b64_e32 v[12:13], 0
	v_mov_b64_e32 v[14:15], 0
	v_mov_b64_e32 v[24:25], 0
	v_mov_b64_e32 v[26:27], 0
	v_mov_b64_e32 v[28:29], 0
	v_mov_b64_e32 v[30:31], 0
	v_mov_b64_e32 v[40:41], 0
	v_mov_b64_e32 v[42:43], 0
	v_mov_b64_e32 v[44:45], 0
	v_mov_b64_e32 v[46:47], 0
	v_mov_b64_e32 v[16:17], 0
	v_mov_b64_e32 v[18:19], 0
	v_mov_b64_e32 v[20:21], 0
	v_mov_b64_e32 v[22:23], 0
	v_mov_b64_e32 v[32:33], 0
	v_mov_b64_e32 v[34:35], 0
	v_mov_b64_e32 v[36:37], 0
	v_mov_b64_e32 v[38:39], 0
	v_mov_b64_e32 v[48:49], 0
	v_mov_b64_e32 v[50:51], 0
	v_mov_b64_e32 v[52:53], 0
	v_mov_b64_e32 v[54:55], 0
	v_mov_b64_e32 v[56:57], 0
	v_mov_b64_e32 v[58:59], 0
	v_mov_b64_e32 v[60:61], 0
	v_mov_b64_e32 v[62:63], 0
	v_mov_b64_e32 v[64:65], 0
	v_mov_b64_e32 v[66:67], 0
	v_mov_b64_e32 v[68:69], 0
	v_mov_b64_e32 v[70:71], 0
	v_mov_b64_e32 v[72:73], 0
	v_mov_b64_e32 v[74:75], 0
	v_mov_b64_e32 v[76:77], 0
	v_mov_b64_e32 v[78:79], 0
	v_mov_b64_e32 v[88:89], 0
	v_mov_b64_e32 v[90:91], 0
	v_mov_b64_e32 v[92:93], 0
	v_mov_b64_e32 v[94:95], 0
	v_mov_b64_e32 v[104:105], 0
	v_mov_b64_e32 v[106:107], 0
	v_mov_b64_e32 v[108:109], 0
	v_mov_b64_e32 v[110:111], 0
	v_mov_b64_e32 v[80:81], 0
	v_mov_b64_e32 v[82:83], 0
	v_mov_b64_e32 v[84:85], 0
	v_mov_b64_e32 v[86:87], 0
	v_mov_b64_e32 v[96:97], 0
	v_mov_b64_e32 v[98:99], 0
	v_mov_b64_e32 v[100:101], 0
	v_mov_b64_e32 v[102:103], 0
	v_mov_b64_e32 v[112:113], 0
	v_mov_b64_e32 v[114:115], 0
	v_mov_b64_e32 v[116:117], 0
	v_mov_b64_e32 v[118:119], 0
	v_mov_b64_e32 v[120:121], 0
	v_mov_b64_e32 v[122:123], 0
	v_mov_b64_e32 v[124:125], 0
	v_mov_b64_e32 v[126:127], 0

; template <bool FIRST, bool MASKED>
; DI void attn2_step(f32x16 (&o)[2][2], float (&m_ref)[2], float (&lsum)[2], const bf16x8 (&qf)[2][4], const lchar* Kl, const lchar* Vl, int lane, int kp0, int qw0, float m_init, float l0) {
;     ...
;     bf16x8 kf[4][2];
; #pragma unroll
;     for (int ks = 0; ks < 4; ++ks)
; #pragma unroll
;         for (int kt = 0; kt < 2; ++kt) kf[ks][kt] = *(const LAS bf16x8*)(Kl + (32 * kt + l31) * KSTR + ks * 32 + h * 16);
;     f32x16 sc[2][2];
; #pragma unroll
;     for (int q = 0; q < 2; ++q) {
;         const float init = FIRST ? opaque0() : -m_ref[q];
; #pragma unroll
;         for (int kt = 0; kt < 2; ++kt)
; #pragma unroll
;             for (int i = 0; i < 16; ++i) sc[q][kt][i] = init;
; #pragma unroll
;         for (int ks = 0; ks < 4; ++ks)
; #pragma unroll
;             for (int kt = 0; kt < 2; ++kt) sc[q][kt] = MFMA32(kf[ks][kt], qf[q][ks], sc[q][kt]);
;     }
;     if (MASKED && kp0 >= 0 && !(kp0 >= qw0 + 63 - 128 && kp0 + 63 <= qw0 + 128)) {
; #pragma unroll
;         for (int q = 0; q < 2; ++q) {
;             const int qpos = qw0 + q * 32 + l31;
; #pragma unroll
;             for (int kt = 0; kt < 2; ++kt)
; #pragma unroll
;                 for (int i = 0; i < 16; ++i) {
;                     const int diff = qpos - (kp0 + 32 * kt + crow(i, h));
;                     if (diff > 128 || diff < -128) sc[q][kt][i] = -1e30f;
;                 }
;         }
;     }
;     float mx[2];
; #pragma unroll
;     for (int q = 0; q < 2; ++q) {
;         float m = fmaxf(sc[q][0][0], sc[q][1][0]);
; #pragma unroll
;         for (int i = 1; i < 16; ++i) m = fmaxf(m, fmaxf(sc[q][0][i], sc[q][1][i]));
;         mx[q] = fmaxf(m, shx(m, 32, lane));
;     }
;     if (FIRST) {
; #pragma unroll
;         for (int q = 0; q < 2; ++q) {
;             m_ref[q] = fmaxf(m_init, mx[q]);
;             lsum[q] = (h == 0) ? l0 * fast_exp2(m_init - m_ref[q]) : 0.f;
; #pragma unroll
;             for (int kt = 0; kt < 2; ++kt)
; #pragma unroll
;                 for (int i = 0; i < 16; ++i) sc[q][kt][i] -= m_ref[q];
;         }
;     } else if (__builtin_amdgcn_ballot_w64(fmaxf(mx[0], mx[1]) > ATT_THR) != 0ull) {
; template <bool MASKED> ...
;     ...
;     for (int it = 1; it < ntiles; ++it) {
;         *(LAS u32x4*)(Kbase + ((it + 1) & 1) * KV_K + koff) = rk; *(LAS u32x4*)(Vbase + ((it + 1) & 1) * VB + voff) = rv;
;         const int i2 = min(it + 2, ntiles - 1);
.LBB0_192:
	s_and_b32 s26, s22, 1
	s_mul_i32 s27, s26, 0x2400
	s_add_i32 s23, s22, -1
	v_add_u32_e32 v64, s27, v176
	s_mulk_i32 s26, 0x3000
	s_waitcnt vmcnt(1)
	ds_write_b128 v64, v[162:165]
	v_add_u32_e32 v64, s26, v178
	s_min_i32 s26, s23, 0x41
	s_cmp_lt_u32 s23, 62
	s_cselect_b32 s27, 2, 0xffffffc2
	s_cselect_b32 s36, s1, s2
	s_and_b32 s23, s23, 1
	s_mul_i32 s37, s23, 0x2400
	s_waitcnt vmcnt(0)
	ds_write_b128 v64, v[166:169] offset:18432
	v_or_b32_e32 v64, s37, v128
	v_add_u32_e32 v65, v64, v179
	v_add_u32_e32 v64, v64, v189
	ds_read_b128 v[162:165], v65
	ds_read_b128 v[192:195], v65 offset:32
	ds_read_b128 v[208:211], v64
	ds_read_b128 v[212:215], v64 offset:32
	s_add_i32 s27, s27, s26
	v_xor_b32_e32 v80, 0x80000000, v181
	s_lshl_b32 s26, s27, 6
	v_mov_b32_e32 v81, v80
	v_mov_b64_e32 v[82:83], v[80:81]
	v_mov_b64_e32 v[84:85], v[80:81]
	v_mov_b64_e32 v[86:87], v[80:81]
	v_mov_b64_e32 v[88:89], v[80:81]
	v_mov_b64_e32 v[90:91], v[80:81]
	v_mov_b64_e32 v[92:93], v[80:81]
	v_mov_b64_e32 v[94:95], v[80:81]
	ds_read_b128 v[216:219], v65 offset:64
	ds_read_b128 v[220:223], v65 offset:96
	ds_read_b128 v[224:227], v64 offset:64
	ds_read_b128 v[228:231], v64 offset:96
	s_add_i32 s26, s26, s36
	v_xor_b32_e32 v64, 0x80000000, v180
	s_waitcnt lgkmcnt(7)
	v_mfma_f32_32x32x16_bf16 v[112:127], v[162:165], v[130:133], v[80:95]
	v_add_u32_e32 v166, s26, v188
	v_mov_b32_e32 v65, v64
	v_mov_b64_e32 v[66:67], v[64:65]
	v_mov_b64_e32 v[68:69], v[64:65]
	s_waitcnt lgkmcnt(5)
	v_mfma_f32_32x32x16_bf16 v[80:95], v[208:211], v[130:133], v[80:95]
	v_mov_b64_e32 v[70:71], v[64:65]
	v_mov_b64_e32 v[72:73], v[64:65]
	v_mov_b64_e32 v[74:75], v[64:65]
	v_mov_b64_e32 v[76:77], v[64:65]
	v_mov_b64_e32 v[78:79], v[64:65]
	v_mfma_f32_32x32x16_bf16 v[112:127], v[192:195], v[134:137], v[112:127]
	s_nop 0
	v_mfma_f32_32x32x16_bf16 v[96:111], v[162:165], v[146:149], v[64:79]
	v_mad_i64_i32 v[162:163], s[26:27], s30, v166, 0
	v_lshlrev_b64 v[162:163], 1, v[162:163]
	v_lshl_add_u64 v[164:165], v[184:185], 0, v[162:163]
	v_lshl_add_u64 v[166:167], v[186:187], 0, v[162:163]
	global_load_dwordx4 v[162:165], v[164:165], off
	s_nop 0
	global_load_dwordx4 v[166:169], v[166:167], off
	s_mov_b32 s26, 0x41000000
	s_waitcnt lgkmcnt(4)
	v_mfma_f32_32x32x16_bf16 v[80:95], v[212:215], v[134:137], v[80:95]
	s_waitcnt lgkmcnt(3)
	v_mfma_f32_32x32x16_bf16 v[112:127], v[216:219], v[138:141], v[112:127]
	s_waitcnt lgkmcnt(1)
	v_mfma_f32_32x32x16_bf16 v[80:95], v[224:227], v[138:141], v[80:95]
	v_mfma_f32_32x32x16_bf16 v[64:79], v[208:211], v[146:149], v[64:79]
	v_mfma_f32_32x32x16_bf16 v[112:127], v[220:223], v[142:145], v[112:127]
	s_waitcnt lgkmcnt(0)
	v_mfma_f32_32x32x16_bf16 v[80:95], v[228:231], v[142:145], v[80:95]
	s_nop 9
	v_max3_f32 v196, v112, v113, v114
	v_max3_f32 v196, v196, v115, v116
	v_mfma_f32_32x32x16_bf16 v[96:111], v[192:195], v[150:153], v[96:111]
	v_max3_f32 v196, v196, v117, v118
	v_max3_f32 v196, v196, v119, v120
	v_max3_f32 v196, v196, v121, v122
	v_mfma_f32_32x32x16_bf16 v[64:79], v[212:215], v[150:153], v[64:79]
	v_max3_f32 v196, v196, v123, v124
	v_max3_f32 v196, v196, v125, v126
	v_max3_f32 v196, v196, v127, v80
	v_mfma_f32_32x32x16_bf16 v[96:111], v[216:219], v[154:157], v[96:111]
	v_max3_f32 v196, v196, v81, v82
	v_max3_f32 v196, v196, v83, v84
	v_max3_f32 v196, v196, v85, v86
	v_mfma_f32_32x32x16_bf16 v[64:79], v[224:227], v[154:157], v[64:79]
	v_max3_f32 v196, v196, v87, v88
	v_max3_f32 v196, v196, v89, v90
	v_max3_f32 v196, v196, v91, v92
	v_mfma_f32_32x32x16_bf16 v[96:111], v[220:223], v[158:161], v[96:111]
	v_max3_f32 v196, v196, v93, v94
	v_max_f32_e32 v192, v196, v95
	v_mfma_f32_32x32x16_bf16 v[64:79], v[228:231], v[158:161], v[64:79]
	v_mov_b32_e32 v193, v192
	s_mulk_i32 s23, 0x3000
	v_or_b32_e32 v244, s23, v191
	v_permlane32_swap_b32_e32 v193, v192
	v_max_f32_e32 v193, v192, v193
	ds_read_b64_tr_b16 v[208:209], v244 offset:18432
	ds_read_b64_tr_b16 v[210:211], v244 offset:19968
	ds_read_b64_tr_b16 v[212:213], v244 offset:18496
	ds_read_b64_tr_b16 v[214:215], v244 offset:20032
	ds_read_b64_tr_b16 v[216:217], v244 offset:21504
	ds_read_b64_tr_b16 v[218:219], v244 offset:23040
	ds_read_b64_tr_b16 v[220:221], v244 offset:21568
	ds_read_b64_tr_b16 v[222:223], v244 offset:23104
	v_max3_f32 v194, v96, v97, v98
	v_max3_f32 v194, v194, v99, v100
	v_max3_f32 v194, v194, v101, v102
	v_max3_f32 v194, v194, v103, v104
	v_max3_f32 v194, v194, v105, v106
	v_max3_f32 v194, v194, v107, v108
	v_max3_f32 v194, v194, v109, v110
	v_max3_f32 v194, v194, v111, v64
	v_max3_f32 v194, v194, v65, v66
	v_max3_f32 v194, v194, v67, v68
	v_max3_f32 v194, v194, v69, v70
	v_max3_f32 v194, v194, v71, v72
	v_max3_f32 v194, v194, v73, v74
	v_max3_f32 v194, v194, v75, v76
	v_max3_f32 v194, v194, v77, v78
	v_max_f32_e32 v194, v194, v79
	v_mov_b32_e32 v195, v194
	s_nop 1
	v_permlane32_swap_b32_e32 v195, v194
	s_waitcnt lgkmcnt(0)
	v_max_f32_e32 v192, v194, v195
	ds_read_b64_tr_b16 v[224:225], v244 offset:24576
	ds_read_b64_tr_b16 v[226:227], v244 offset:26112
	ds_read_b64_tr_b16 v[228:229], v244 offset:24640
	ds_read_b64_tr_b16 v[230:231], v244 offset:26176
	ds_read_b64_tr_b16 v[232:233], v244 offset:27648
	ds_read_b64_tr_b16 v[234:235], v244 offset:29184
	ds_read_b64_tr_b16 v[236:237], v244 offset:27712
	ds_read_b64_tr_b16 v[238:239], v244 offset:29248
	v_max_f32_e32 v194, v193, v192
	v_cmp_lt_f32_e32 vcc, s26, v194
	s_cbranch_vccz .LBB0_191
; DI float fast_exp2(float x) { return __builtin_amdgcn_exp2f(x); }
; template <bool FIRST, bool MASKED>
; DI void attn2_step(f32x16 (&o)[2][2], float (&m_ref)[2], float (&lsum)[2], const bf16x8 (&qf)[2][4], const lchar* Kl, const lchar* Vl, int lane, int kp0, int qw0, float m_init, float l0) {
;     ...
;     } else if (__builtin_amdgcn_ballot_w64(fmaxf(mx[0], mx[1]) > ATT_THR) != 0ull) {
; #pragma unroll
;         for (int q = 0; q < 2; ++q) {
;             const float delta = fmaxf(mx[q], 0.f), alpha = fast_exp2(-delta);
; #pragma unroll
;             for (int dt = 0; dt < 2; ++dt)
; #pragma unroll
;                 for (int i = 0; i < 16; ++i) o[q][dt][i] *= alpha;
;             lsum[q] *= alpha;
; #pragma unroll
;             for (int kt = 0; kt < 2; ++kt)
; #pragma unroll
;                 for (int i = 0; i < 16; ++i) sc[q][kt][i] -= delta;
;             m_ref[q] += delta;
;         }
;     }
	v_max_f32_e32 v193, v193, v193
	v_max_f32_e32 v192, v192, v192
	v_max_f32_e32 v194, 0, v193
	v_max_f32_e32 v192, 0, v192
	v_exp_f32_e64 v196, -v194
	v_exp_f32_e64 v200, -v192
	v_pk_add_f32 v[96:97], v[96:97], v[192:193] op_sel_hi:[1,0] neg_lo:[0,1] neg_hi:[0,1]
	v_pk_add_f32 v[98:99], v[98:99], v[192:193] op_sel_hi:[1,0] neg_lo:[0,1] neg_hi:[0,1]
	v_pk_add_f32 v[100:101], v[100:101], v[192:193] op_sel_hi:[1,0] neg_lo:[0,1] neg_hi:[0,1]
	v_pk_mul_f32 v[30:31], v[30:31], v[200:201] op_sel_hi:[1,0]
	v_pk_mul_f32 v[28:29], v[28:29], v[200:201] op_sel_hi:[1,0]
	v_pk_mul_f32 v[26:27], v[26:27], v[200:201] op_sel_hi:[1,0]
	v_pk_mul_f32 v[24:25], v[24:25], v[200:201] op_sel_hi:[1,0]
	v_pk_mul_f32 v[22:23], v[22:23], v[200:201] op_sel_hi:[1,0]
	v_pk_mul_f32 v[20:21], v[20:21], v[200:201] op_sel_hi:[1,0]
	v_pk_mul_f32 v[18:19], v[18:19], v[200:201] op_sel_hi:[1,0]
	v_pk_mul_f32 v[16:17], v[16:17], v[200:201] op_sel_hi:[1,0]
	v_pk_mul_f32 v[14:15], v[14:15], v[200:201] op_sel_hi:[1,0]
	v_pk_mul_f32 v[12:13], v[12:13], v[200:201] op_sel_hi:[1,0]
	v_pk_mul_f32 v[10:11], v[10:11], v[200:201] op_sel_hi:[1,0]
	v_pk_mul_f32 v[8:9], v[8:9], v[200:201] op_sel_hi:[1,0]
	v_pk_mul_f32 v[6:7], v[6:7], v[200:201] op_sel_hi:[1,0]
	v_pk_mul_f32 v[4:5], v[4:5], v[200:201] op_sel_hi:[1,0]
	v_pk_mul_f32 v[2:3], v[2:3], v[200:201] op_sel_hi:[1,0]
	v_pk_mul_f32 v[0:1], v[0:1], v[200:201] op_sel_hi:[1,0]
	v_mov_b32_e32 v201, v196
	v_pk_add_f32 v[102:103], v[102:103], v[192:193] op_sel_hi:[1,0] neg_lo:[0,1] neg_hi:[0,1]
	v_pk_add_f32 v[104:105], v[104:105], v[192:193] op_sel_hi:[1,0] neg_lo:[0,1] neg_hi:[0,1]
	v_pk_add_f32 v[106:107], v[106:107], v[192:193] op_sel_hi:[1,0] neg_lo:[0,1] neg_hi:[0,1]
	v_pk_add_f32 v[108:109], v[108:109], v[192:193] op_sel_hi:[1,0] neg_lo:[0,1] neg_hi:[0,1]
	v_pk_add_f32 v[110:111], v[110:111], v[192:193] op_sel_hi:[1,0] neg_lo:[0,1] neg_hi:[0,1]
	v_pk_add_f32 v[64:65], v[64:65], v[192:193] op_sel_hi:[1,0] neg_lo:[0,1] neg_hi:[0,1]
	v_pk_add_f32 v[66:67], v[66:67], v[192:193] op_sel_hi:[1,0] neg_lo:[0,1] neg_hi:[0,1]
	v_pk_add_f32 v[68:69], v[68:69], v[192:193] op_sel_hi:[1,0] neg_lo:[0,1] neg_hi:[0,1]
	v_pk_add_f32 v[70:71], v[70:71], v[192:193] op_sel_hi:[1,0] neg_lo:[0,1] neg_hi:[0,1]
	v_pk_add_f32 v[72:73], v[72:73], v[192:193] op_sel_hi:[1,0] neg_lo:[0,1] neg_hi:[0,1]
	v_pk_add_f32 v[74:75], v[74:75], v[192:193] op_sel_hi:[1,0] neg_lo:[0,1] neg_hi:[0,1]
	v_pk_add_f32 v[76:77], v[76:77], v[192:193] op_sel_hi:[1,0] neg_lo:[0,1] neg_hi:[0,1]
	v_pk_add_f32 v[78:79], v[78:79], v[192:193] op_sel_hi:[1,0] neg_lo:[0,1] neg_hi:[0,1]
	v_mov_b32_e32 v193, v194
	v_pk_mul_f32 v[46:47], v[46:47], v[196:197] op_sel_hi:[1,0]
	v_pk_mul_f32 v[44:45], v[44:45], v[196:197] op_sel_hi:[1,0]
	v_pk_mul_f32 v[42:43], v[42:43], v[196:197] op_sel_hi:[1,0]
	v_pk_mul_f32 v[40:41], v[40:41], v[196:197] op_sel_hi:[1,0]
	v_pk_mul_f32 v[38:39], v[38:39], v[196:197] op_sel_hi:[1,0]
	v_pk_mul_f32 v[36:37], v[36:37], v[196:197] op_sel_hi:[1,0]
	v_pk_mul_f32 v[34:35], v[34:35], v[196:197] op_sel_hi:[1,0]
	v_pk_mul_f32 v[32:33], v[32:33], v[196:197] op_sel_hi:[1,0]
	v_pk_mul_f32 v[62:63], v[62:63], v[196:197] op_sel_hi:[1,0]
	v_pk_mul_f32 v[60:61], v[60:61], v[196:197] op_sel_hi:[1,0]
	v_pk_mul_f32 v[58:59], v[58:59], v[196:197] op_sel_hi:[1,0]
	v_pk_mul_f32 v[56:57], v[56:57], v[196:197] op_sel_hi:[1,0]
	v_pk_mul_f32 v[54:55], v[54:55], v[196:197] op_sel_hi:[1,0]
	v_pk_mul_f32 v[52:53], v[52:53], v[196:197] op_sel_hi:[1,0]
	v_pk_mul_f32 v[50:51], v[50:51], v[196:197] op_sel_hi:[1,0]
	v_pk_mul_f32 v[48:49], v[48:49], v[196:197] op_sel_hi:[1,0]
	v_pk_add_f32 v[112:113], v[112:113], v[194:195] op_sel_hi:[1,0] neg_lo:[0,1] neg_hi:[0,1]
	v_pk_add_f32 v[114:115], v[114:115], v[194:195] op_sel_hi:[1,0] neg_lo:[0,1] neg_hi:[0,1]
	v_pk_add_f32 v[116:117], v[116:117], v[194:195] op_sel_hi:[1,0] neg_lo:[0,1] neg_hi:[0,1]
	v_pk_add_f32 v[118:119], v[118:119], v[194:195] op_sel_hi:[1,0] neg_lo:[0,1] neg_hi:[0,1]
	v_pk_add_f32 v[120:121], v[120:121], v[194:195] op_sel_hi:[1,0] neg_lo:[0,1] neg_hi:[0,1]
	v_pk_add_f32 v[122:123], v[122:123], v[194:195] op_sel_hi:[1,0] neg_lo:[0,1] neg_hi:[0,1]
	v_pk_add_f32 v[124:125], v[124:125], v[194:195] op_sel_hi:[1,0] neg_lo:[0,1] neg_hi:[0,1]
	v_pk_add_f32 v[126:127], v[126:127], v[194:195] op_sel_hi:[1,0] neg_lo:[0,1] neg_hi:[0,1]
	v_pk_add_f32 v[80:81], v[80:81], v[194:195] op_sel_hi:[1,0] neg_lo:[0,1] neg_hi:[0,1]
	v_pk_add_f32 v[82:83], v[82:83], v[194:195] op_sel_hi:[1,0] neg_lo:[0,1] neg_hi:[0,1]
	v_pk_add_f32 v[84:85], v[84:85], v[194:195] op_sel_hi:[1,0] neg_lo:[0,1] neg_hi:[0,1]
	v_pk_add_f32 v[86:87], v[86:87], v[194:195] op_sel_hi:[1,0] neg_lo:[0,1] neg_hi:[0,1]
	v_pk_add_f32 v[88:89], v[88:89], v[194:195] op_sel_hi:[1,0] neg_lo:[0,1] neg_hi:[0,1]
	v_pk_add_f32 v[90:91], v[90:91], v[194:195] op_sel_hi:[1,0] neg_lo:[0,1] neg_hi:[0,1]
	v_pk_add_f32 v[92:93], v[92:93], v[194:195] op_sel_hi:[1,0] neg_lo:[0,1] neg_hi:[0,1]
	v_pk_add_f32 v[94:95], v[94:95], v[194:195] op_sel_hi:[1,0] neg_lo:[0,1] neg_hi:[0,1]
	v_pk_mul_f32 v[182:183], v[182:183], v[200:201]
	v_pk_add_f32 v[180:181], v[180:181], v[192:193]
	s_branch .LBB0_191

; template <class Epi, class Sched, bool ALIGN_EPI = false, bool SP2 = false>
; __device__ __forceinline__ void gemm_phase(LAS unsigned char* lds, const Gemm g, const Sched& S, const Epi& E) {
;     ...
;         const bool has_next = S.next(ui + 1, nxt);
;         const char* nA = has_next ? (const char*)g.A + (size_t)nxt.pm * g.a_tstep : cA; const char* nB = has_next ? (const char*)g.Bt + (size_t)nxt.pn * tstep : cB;
;     ...
; #pragma unroll
;         for (int a = 0; a < 2; ++a)
; #pragma unroll
;             for (int b = 0; b < 2; ++b)
; #pragma unroll
;                 for (int m = 0; m < 4; ++m)
; #pragma unroll
;                     for (int n = 0; n < 2; ++n) acc[a][b][m][n] = (f32x4){0.f, 0.f, 0.f, 0.f};
;         cur = nxt; cA = nA; cB = nB; ++ui;
.LBB0_333:
	v_readlane_b32 s48, v252, 31
	v_readlane_b32 s49, v252, 32
	s_ashr_i32 s35, s34, 31
	s_mov_b32 s55, -2
	v_mov_b64_e32 v[0:1], s[48:49]
	v_cmp_lt_i64_e32 vcc, s[46:47], v[0:1]
	s_lshl_b64 s[46:47], s[34:35], 19
	s_add_u32 s46, s78, s46
	s_addc_u32 s47, s79, s47
	s_and_b64 s[48:49], vcc, exec
	s_cselect_b32 s35, s47, s43
	s_cselect_b32 s41, s46, s42
	s_ashr_i32 s31, s30, 31
	s_lshl_b64 s[48:49], s[30:31], 19
	s_add_u32 s48, s66, s48
	s_addc_u32 s49, s67, s49
	s_and_b64 s[50:51], vcc, exec
	s_cselect_b32 s31, s49, s45
	s_cselect_b32 s52, s48, s44
	s_add_u32 s42, s42, 0x40080
	s_addc_u32 s43, s43, 0
	s_add_u32 s53, s44, 0x100
	v_mov_b64_e32 v[0:1], 0
	s_addc_u32 s54, s45, 0
	v_mov_b64_e32 v[2:3], 0
	v_mov_b64_e32 v[4:5], 0
	v_mov_b64_e32 v[6:7], 0
	v_mov_b64_e32 v[16:17], 0
	v_mov_b64_e32 v[18:19], 0
	v_mov_b64_e32 v[20:21], 0
	v_mov_b64_e32 v[22:23], 0
	v_mov_b64_e32 v[32:33], 0
	v_mov_b64_e32 v[34:35], 0
	v_mov_b64_e32 v[36:37], 0
	v_mov_b64_e32 v[38:39], 0
	v_mov_b64_e32 v[48:49], 0
	v_mov_b64_e32 v[50:51], 0
	v_mov_b64_e32 v[52:53], 0
	v_mov_b64_e32 v[54:55], 0
	v_mov_b64_e32 v[8:9], 0
	v_mov_b64_e32 v[10:11], 0
	v_mov_b64_e32 v[12:13], 0
	v_mov_b64_e32 v[14:15], 0
	v_mov_b64_e32 v[24:25], 0
	v_mov_b64_e32 v[26:27], 0
	v_mov_b64_e32 v[28:29], 0
	v_mov_b64_e32 v[30:31], 0
	v_mov_b64_e32 v[40:41], 0
	v_mov_b64_e32 v[42:43], 0
	v_mov_b64_e32 v[44:45], 0
	v_mov_b64_e32 v[46:47], 0
	v_mov_b64_e32 v[56:57], 0
	v_mov_b64_e32 v[58:59], 0
	v_mov_b64_e32 v[60:61], 0
	v_mov_b64_e32 v[62:63], 0
	v_mov_b64_e32 v[76:77], 0
	v_mov_b64_e32 v[78:79], 0
	v_mov_b64_e32 v[84:85], 0
	v_mov_b64_e32 v[86:87], 0
	v_mov_b64_e32 v[96:97], 0
	v_mov_b64_e32 v[98:99], 0
	v_mov_b64_e32 v[100:101], 0
	v_mov_b64_e32 v[102:103], 0
	v_mov_b64_e32 v[112:113], 0
	v_mov_b64_e32 v[114:115], 0
	v_mov_b64_e32 v[116:117], 0
	v_mov_b64_e32 v[118:119], 0
	v_mov_b64_e32 v[130:131], 0
	v_mov_b64_e32 v[132:133], 0
	v_mov_b64_e32 v[134:135], 0
	v_mov_b64_e32 v[136:137], 0
	v_mov_b64_e32 v[88:89], 0
	v_mov_b64_e32 v[90:91], 0
	v_mov_b64_e32 v[92:93], 0
	v_mov_b64_e32 v[94:95], 0
	v_mov_b64_e32 v[104:105], 0
	v_mov_b64_e32 v[106:107], 0
	v_mov_b64_e32 v[108:109], 0
	v_mov_b64_e32 v[110:111], 0
	v_mov_b64_e32 v[120:121], 0
	v_mov_b64_e32 v[122:123], 0
	v_mov_b64_e32 v[124:125], 0
	v_mov_b64_e32 v[126:127], 0
	v_mov_b64_e32 v[138:139], 0
	v_mov_b64_e32 v[140:141], 0
	v_mov_b64_e32 v[142:143], 0
	v_mov_b64_e32 v[144:145], 0
	s_waitcnt vmcnt(0)
